# nt hint on the once-read w_ada loads of the modulation pass (P0 and QKV-phase filler)
# speedup vs baseline: 1.0213x; 1.0024x over previous
.LBB0_24:
	s_mul_hi_i32 s12, s41, 0x2aaaaaab
	s_lshr_b32 s13, s12, 31
	s_ashr_i32 s12, s12, 5
	s_add_i32 s12, s12, s13
	s_mul_i32 s13, s12, 0xc0
	s_sub_i32 s22, s41, s13
	s_ashr_i32 s13, s12, 31
	s_lshl_b64 s[20:21], s[12:13], 10
	v_lshl_add_u64 v[2:3], s[20:21], 0, v[14:15]
	s_lshl_b32 s14, s22, 5
	v_mad_u64_u32 v[4:5], s[20:21], v2, s24, v[22:23]
	v_mad_i32_i24 v5, v3, s24, v5
	s_ashr_i32 s15, s14, 31
	v_lshl_add_u64 v[2:3], s[14:15], 2, v[4:5]
	v_lshl_add_u64 v[26:27], v[2:3], 0, v[24:25]
	v_add_co_u32_e32 v2, vcc, s25, v26
	global_load_dwordx4 v[6:9], v[26:27], off nt
	s_nop 0
	v_addc_co_u32_e32 v3, vcc, 0, v27, vcc
	v_add_co_u32_e32 v10, vcc, s26, v26
	global_load_dwordx4 v[2:5], v[2:3], off nt
	s_nop 0
	v_addc_co_u32_e32 v11, vcc, 0, v27, vcc
	global_load_dwordx4 v[34:37], v[10:11], off nt
	v_add_co_u32_e32 v10, vcc, s27, v26
	s_nop 1
	v_addc_co_u32_e32 v11, vcc, 0, v27, vcc
	global_load_dwordx4 v[38:41], v[10:11], off nt
	v_add_co_u32_e32 v10, vcc, s28, v26
	ds_read2st64_b32 v[54:55], v1 offset1:1
	ds_read2st64_b32 v[56:57], v1 offset0:2 offset1:3
	ds_read2st64_b32 v[58:59], v1 offset0:4 offset1:5
	ds_read2st64_b32 v[60:61], v1 offset0:6 offset1:7
	ds_read2st64_b32 v[62:63], v1 offset0:16 offset1:17
	ds_read2st64_b32 v[64:65], v1 offset0:18 offset1:19
	ds_read2st64_b32 v[66:67], v1 offset0:20 offset1:21
	ds_read2st64_b32 v[68:69], v1 offset0:22 offset1:23
	v_addc_co_u32_e32 v11, vcc, 0, v27, vcc
	global_load_dwordx4 v[42:45], v[10:11], off nt
	v_add_co_u32_e32 v10, vcc, s29, v26
	ds_read2st64_b32 v[70:71], v1 offset0:32 offset1:33
	ds_read2st64_b32 v[72:73], v1 offset0:34 offset1:35
	ds_read2st64_b32 v[74:75], v1 offset0:36 offset1:37
	ds_read2st64_b32 v[28:29], v1 offset0:38 offset1:39
	ds_read2st64_b32 v[76:77], v1 offset0:48 offset1:49
	ds_read2st64_b32 v[78:79], v1 offset0:50 offset1:51
	ds_read2st64_b32 v[80:81], v1 offset0:52 offset1:53
	ds_read2st64_b32 v[30:31], v1 offset0:54 offset1:55
	v_addc_co_u32_e32 v11, vcc, 0, v27, vcc
	global_load_dwordx4 v[46:49], v[10:11], off nt
	v_add_co_u32_e32 v94, vcc, s30, v26
	ds_read2st64_b32 v[82:83], v1 offset0:64 offset1:65
	ds_read2st64_b32 v[84:85], v1 offset0:66 offset1:67
	ds_read2st64_b32 v[86:87], v1 offset0:68 offset1:69
	ds_read2st64_b32 v[32:33], v1 offset0:70 offset1:71
	v_addc_co_u32_e32 v95, vcc, 0, v27, vcc
	v_add_co_u32_e32 v96, vcc, s31, v26
	s_waitcnt lgkmcnt(14)
	v_mov_b32_e32 v16, v55
	v_addc_co_u32_e32 v97, vcc, 0, v27, vcc
	global_load_dwordx4 v[50:53], v[94:95], off nt
	global_load_dwordx4 v[10:13], v[96:97], off nt
	v_mov_b32_e32 v88, v63
	s_waitcnt lgkmcnt(11)
	v_mov_b32_e32 v90, v71
	s_waitcnt lgkmcnt(7)
	v_mov_b32_e32 v92, v77
	s_waitcnt vmcnt(7)
	v_pk_fma_f32 v[94:95], v[8:9], v[54:55], 0 op_sel_hi:[1,0,0]
	v_pk_fma_f32 v[54:55], v[6:7], v[54:55], 0 op_sel_hi:[1,0,0]
	v_pk_fma_f32 v[96:97], v[8:9], v[62:63], 0 op_sel_hi:[1,0,0]
	v_pk_fma_f32 v[62:63], v[6:7], v[62:63], 0 op_sel_hi:[1,0,0]
	v_pk_fma_f32 v[98:99], v[8:9], v[70:71], 0 op_sel_hi:[1,0,0]
	v_pk_fma_f32 v[70:71], v[6:7], v[70:71], 0 op_sel_hi:[1,0,0]
	v_pk_fma_f32 v[100:101], v[8:9], v[76:77], 0 op_sel_hi:[1,0,0]
	v_pk_fma_f32 v[76:77], v[6:7], v[76:77], 0 op_sel_hi:[1,0,0]
	s_waitcnt lgkmcnt(3)
	v_pk_fma_f32 v[6:7], v[6:7], v[82:83], 0 op_sel_hi:[1,0,0]
	s_waitcnt vmcnt(6)
	v_pk_fma_f32 v[94:95], v[4:5], v[16:17], v[94:95] op_sel_hi:[1,0,1]
	v_pk_fma_f32 v[54:55], v[2:3], v[16:17], v[54:55] op_sel_hi:[1,0,1]
	v_mov_b32_e32 v16, v83
	v_pk_fma_f32 v[8:9], v[8:9], v[82:83], 0 op_sel_hi:[1,0,0]
	v_pk_fma_f32 v[62:63], v[2:3], v[88:89], v[62:63] op_sel_hi:[1,0,1]
	v_pk_fma_f32 v[70:71], v[2:3], v[90:91], v[70:71] op_sel_hi:[1,0,1]
	v_pk_fma_f32 v[76:77], v[2:3], v[92:93], v[76:77] op_sel_hi:[1,0,1]
	v_pk_fma_f32 v[2:3], v[2:3], v[16:17], v[6:7] op_sel_hi:[1,0,1]
	v_pk_fma_f32 v[96:97], v[4:5], v[88:89], v[96:97] op_sel_hi:[1,0,1]
	v_pk_fma_f32 v[88:89], v[4:5], v[90:91], v[98:99] op_sel_hi:[1,0,1]
	v_pk_fma_f32 v[90:91], v[4:5], v[92:93], v[100:101] op_sel_hi:[1,0,1]
	v_pk_fma_f32 v[4:5], v[4:5], v[16:17], v[8:9] op_sel_hi:[1,0,1]
	s_waitcnt vmcnt(5)
	v_pk_fma_f32 v[6:7], v[36:37], v[56:57], v[94:95] op_sel_hi:[1,0,1]
	v_pk_fma_f32 v[8:9], v[34:35], v[56:57], v[54:55] op_sel_hi:[1,0,1]
	v_pk_fma_f32 v[62:63], v[34:35], v[64:65], v[62:63] op_sel_hi:[1,0,1]
	v_pk_fma_f32 v[70:71], v[34:35], v[72:73], v[70:71] op_sel_hi:[1,0,1]
	v_pk_fma_f32 v[76:77], v[34:35], v[78:79], v[76:77] op_sel_hi:[1,0,1]
	s_waitcnt lgkmcnt(2)
	v_pk_fma_f32 v[34:35], v[34:35], v[84:85], v[2:3] op_sel_hi:[1,0,1]
	v_mov_b32_e32 v2, v57
	s_waitcnt vmcnt(4)
	v_pk_fma_f32 v[6:7], v[40:41], v[2:3], v[6:7] op_sel_hi:[1,0,1]
	v_pk_fma_f32 v[8:9], v[38:39], v[2:3], v[8:9] op_sel_hi:[1,0,1]
	v_add_co_u32_e32 v2, vcc, s33, v26
	v_pk_fma_f32 v[54:55], v[36:37], v[64:65], v[96:97] op_sel_hi:[1,0,1]
	s_nop 0
	v_addc_co_u32_e32 v3, vcc, 0, v27, vcc
	v_pk_fma_f32 v[82:83], v[36:37], v[72:73], v[88:89] op_sel_hi:[1,0,1]
	v_pk_fma_f32 v[88:89], v[36:37], v[78:79], v[90:91] op_sel_hi:[1,0,1]
	v_pk_fma_f32 v[36:37], v[36:37], v[84:85], v[4:5] op_sel_hi:[1,0,1]
	global_load_dwordx4 v[2:5], v[2:3], off nt
	v_mov_b32_e32 v16, v65
	v_pk_fma_f32 v[54:55], v[40:41], v[16:17], v[54:55] op_sel_hi:[1,0,1]
	v_pk_fma_f32 v[56:57], v[38:39], v[16:17], v[62:63] op_sel_hi:[1,0,1]
	v_mov_b32_e32 v16, v73
	v_pk_fma_f32 v[62:63], v[40:41], v[16:17], v[82:83] op_sel_hi:[1,0,1]
	v_pk_fma_f32 v[64:65], v[38:39], v[16:17], v[70:71] op_sel_hi:[1,0,1]
	v_mov_b32_e32 v16, v79
	v_pk_fma_f32 v[70:71], v[40:41], v[16:17], v[88:89] op_sel_hi:[1,0,1]
	v_pk_fma_f32 v[72:73], v[38:39], v[16:17], v[76:77] op_sel_hi:[1,0,1]
	v_mov_b32_e32 v16, v85
	v_pk_fma_f32 v[36:37], v[40:41], v[16:17], v[36:37] op_sel_hi:[1,0,1]
	v_pk_fma_f32 v[34:35], v[38:39], v[16:17], v[34:35] op_sel_hi:[1,0,1]
	s_waitcnt vmcnt(4)
	v_pk_fma_f32 v[6:7], v[44:45], v[58:59], v[6:7] op_sel_hi:[1,0,1]
	v_mov_b32_e32 v16, v59
	v_pk_fma_f32 v[8:9], v[42:43], v[58:59], v[8:9] op_sel_hi:[1,0,1]
	v_pk_fma_f32 v[38:39], v[44:45], v[66:67], v[54:55] op_sel_hi:[1,0,1]
	v_pk_fma_f32 v[40:41], v[42:43], v[66:67], v[56:57] op_sel_hi:[1,0,1]
	v_pk_fma_f32 v[56:57], v[42:43], v[74:75], v[64:65] op_sel_hi:[1,0,1]
	v_pk_fma_f32 v[64:65], v[42:43], v[80:81], v[72:73] op_sel_hi:[1,0,1]
	s_waitcnt lgkmcnt(1)
	v_pk_fma_f32 v[34:35], v[42:43], v[86:87], v[34:35] op_sel_hi:[1,0,1]
	s_waitcnt vmcnt(3)
	v_pk_fma_f32 v[42:43], v[48:49], v[16:17], v[6:7] op_sel_hi:[1,0,1]
	v_mov_b32_e32 v6, v67
	v_pk_fma_f32 v[54:55], v[44:45], v[74:75], v[62:63] op_sel_hi:[1,0,1]
	v_pk_fma_f32 v[38:39], v[48:49], v[6:7], v[38:39] op_sel_hi:[1,0,1]
	v_pk_fma_f32 v[40:41], v[46:47], v[6:7], v[40:41] op_sel_hi:[1,0,1]
	v_mov_b32_e32 v6, v75
	v_pk_fma_f32 v[62:63], v[44:45], v[80:81], v[70:71] op_sel_hi:[1,0,1]
	v_pk_fma_f32 v[54:55], v[48:49], v[6:7], v[54:55] op_sel_hi:[1,0,1]
	v_pk_fma_f32 v[56:57], v[46:47], v[6:7], v[56:57] op_sel_hi:[1,0,1]
	v_mov_b32_e32 v6, v81
	v_pk_fma_f32 v[36:37], v[44:45], v[86:87], v[36:37] op_sel_hi:[1,0,1]
	v_pk_fma_f32 v[44:45], v[46:47], v[16:17], v[8:9] op_sel_hi:[1,0,1]
	v_pk_fma_f32 v[58:59], v[48:49], v[6:7], v[62:63] op_sel_hi:[1,0,1]
	v_pk_fma_f32 v[62:63], v[46:47], v[6:7], v[64:65] op_sel_hi:[1,0,1]
	v_add_co_u32_e32 v6, vcc, s34, v26
	v_mov_b32_e32 v8, v87
	s_nop 0
	v_addc_co_u32_e32 v7, vcc, 0, v27, vcc
	s_waitcnt vmcnt(2)
	v_pk_fma_f32 v[42:43], v[52:53], v[60:61], v[42:43] op_sel_hi:[1,0,1]
	v_pk_fma_f32 v[44:45], v[50:51], v[60:61], v[44:45] op_sel_hi:[1,0,1]
	v_mov_b32_e32 v16, v61
	v_pk_fma_f32 v[36:37], v[48:49], v[8:9], v[36:37] op_sel_hi:[1,0,1]
	v_pk_fma_f32 v[34:35], v[46:47], v[8:9], v[34:35] op_sel_hi:[1,0,1]
	global_load_dwordx4 v[6:9], v[6:7], off nt
	v_pk_fma_f32 v[46:47], v[52:53], v[68:69], v[38:39] op_sel_hi:[1,0,1]
	v_pk_fma_f32 v[40:41], v[50:51], v[68:69], v[40:41] op_sel_hi:[1,0,1]
	s_waitcnt vmcnt(2)
	v_pk_fma_f32 v[60:61], v[12:13], v[16:17], v[42:43] op_sel_hi:[1,0,1]
	v_pk_fma_f32 v[38:39], v[10:11], v[16:17], v[44:45] op_sel_hi:[1,0,1]
	v_mov_b32_e32 v16, v69
	v_pk_fma_f32 v[48:49], v[52:53], v[28:29], v[54:55] op_sel_hi:[1,0,1]
	v_pk_fma_f32 v[54:55], v[50:51], v[28:29], v[56:57] op_sel_hi:[1,0,1]
	v_pk_fma_f32 v[56:57], v[52:53], v[30:31], v[58:59] op_sel_hi:[1,0,1]
	v_pk_fma_f32 v[58:59], v[50:51], v[30:31], v[62:63] op_sel_hi:[1,0,1]
	s_waitcnt lgkmcnt(0)
	v_pk_fma_f32 v[50:51], v[50:51], v[32:33], v[34:35] op_sel_hi:[1,0,1]
	v_pk_fma_f32 v[34:35], v[10:11], v[16:17], v[40:41] op_sel_hi:[1,0,1]
	v_add_co_u32_e32 v40, vcc, s35, v26
	v_pk_fma_f32 v[52:53], v[52:53], v[32:33], v[36:37] op_sel_hi:[1,0,1]
	s_nop 0
	v_addc_co_u32_e32 v41, vcc, 0, v27, vcc
	v_add_co_u32_e32 v28, vcc, s36, v26
	v_pk_fma_f32 v[36:37], v[12:13], v[16:17], v[46:47] op_sel_hi:[1,0,1]
	global_load_dwordx4 v[40:43], v[40:41], off nt
	v_mov_b32_e32 v16, v29
	v_addc_co_u32_e32 v29, vcc, 0, v27, vcc
	v_pk_fma_f32 v[44:45], v[12:13], v[16:17], v[48:49] op_sel_hi:[1,0,1]
	v_pk_fma_f32 v[46:47], v[10:11], v[16:17], v[54:55] op_sel_hi:[1,0,1]
	v_mov_b32_e32 v16, v31
	global_load_dwordx4 v[28:31], v[28:29], off nt
	v_pk_fma_f32 v[48:49], v[12:13], v[16:17], v[56:57] op_sel_hi:[1,0,1]
	v_pk_fma_f32 v[54:55], v[10:11], v[16:17], v[58:59] op_sel_hi:[1,0,1]
	v_mov_b32_e32 v16, v33
	ds_read2st64_b32 v[56:57], v1 offset0:8 offset1:9
	ds_read2st64_b32 v[58:59], v1 offset0:10 offset1:11
	ds_read2st64_b32 v[62:63], v1 offset0:12 offset1:13
	ds_read2st64_b32 v[64:65], v1 offset0:14 offset1:15
	ds_read2st64_b32 v[66:67], v1 offset0:24 offset1:25
	v_pk_fma_f32 v[50:51], v[10:11], v[16:17], v[50:51] op_sel_hi:[1,0,1]
	v_add_co_u32_e32 v10, vcc, s37, v26
	v_pk_fma_f32 v[52:53], v[12:13], v[16:17], v[52:53] op_sel_hi:[1,0,1]
	s_nop 0
	v_addc_co_u32_e32 v11, vcc, 0, v27, vcc
	v_add_co_u32_e32 v32, vcc, s38, v26
	global_load_dwordx4 v[10:13], v[10:11], off nt
	s_nop 0
	v_addc_co_u32_e32 v33, vcc, 0, v27, vcc
	s_waitcnt vmcnt(4) lgkmcnt(4)
	v_pk_fma_f32 v[68:69], v[2:3], v[56:57], v[38:39] op_sel_hi:[1,0,1]
	ds_read2st64_b32 v[70:71], v1 offset0:26 offset1:27
	ds_read2st64_b32 v[72:73], v1 offset0:28 offset1:29
	ds_read2st64_b32 v[74:75], v1 offset0:30 offset1:31
	s_waitcnt lgkmcnt(3)
	v_pk_fma_f32 v[76:77], v[4:5], v[66:67], v[36:37] op_sel_hi:[1,0,1]
	ds_read2st64_b32 v[78:79], v1 offset0:40 offset1:41
	global_load_dwordx4 v[36:39], v[32:33], off nt
	v_add_co_u32_e32 v32, vcc, s39, v26
	v_pk_fma_f32 v[80:81], v[2:3], v[66:67], v[34:35] op_sel_hi:[1,0,1]
	s_nop 0
	v_addc_co_u32_e32 v33, vcc, 0, v27, vcc
	v_add_co_u32_e32 v26, vcc, s40, v26
	ds_read2st64_b32 v[82:83], v1 offset0:42 offset1:43
	ds_read2st64_b32 v[84:85], v1 offset0:44 offset1:45
	ds_read2st64_b32 v[86:87], v1 offset0:46 offset1:47
	global_load_dwordx4 v[32:35], v[32:33], off nt
	v_addc_co_u32_e32 v27, vcc, 0, v27, vcc
	s_waitcnt lgkmcnt(3)
	v_pk_fma_f32 v[88:89], v[4:5], v[78:79], v[44:45] op_sel_hi:[1,0,1]
	v_pk_fma_f32 v[90:91], v[2:3], v[78:79], v[46:47] op_sel_hi:[1,0,1]
	ds_read2st64_b32 v[92:93], v1 offset0:56 offset1:57
	ds_read2st64_b32 v[94:95], v1 offset0:58 offset1:59
	ds_read2st64_b32 v[96:97], v1 offset0:60 offset1:61
	ds_read2st64_b32 v[98:99], v1 offset0:62 offset1:63
	global_load_dwordx4 v[44:47], v[26:27], off nt
	ds_read2st64_b32 v[100:101], v1 offset0:72 offset1:73
	v_pk_fma_f32 v[60:61], v[4:5], v[56:57], v[60:61] op_sel_hi:[1,0,1]
	v_mov_b32_e32 v16, v57
	s_waitcnt lgkmcnt(4)
	v_pk_fma_f32 v[48:49], v[4:5], v[92:93], v[48:49] op_sel_hi:[1,0,1]
	v_pk_fma_f32 v[54:55], v[2:3], v[92:93], v[54:55] op_sel_hi:[1,0,1]
	s_waitcnt lgkmcnt(0)
	v_pk_fma_f32 v[4:5], v[4:5], v[100:101], v[52:53] op_sel_hi:[1,0,1]
	v_pk_fma_f32 v[2:3], v[2:3], v[100:101], v[50:51] op_sel_hi:[1,0,1]
	ds_read2st64_b32 v[26:27], v1 offset0:74 offset1:75
	ds_read2st64_b32 v[102:103], v1 offset0:76 offset1:77
	ds_read2st64_b32 v[104:105], v1 offset0:78 offset1:79
	s_waitcnt vmcnt(6)
	v_pk_fma_f32 v[50:51], v[8:9], v[16:17], v[60:61] op_sel_hi:[1,0,1]
	v_pk_fma_f32 v[52:53], v[6:7], v[16:17], v[68:69] op_sel_hi:[1,0,1]
	v_mov_b32_e32 v16, v67
	v_pk_fma_f32 v[56:57], v[8:9], v[16:17], v[76:77] op_sel_hi:[1,0,1]
	v_pk_fma_f32 v[60:61], v[6:7], v[16:17], v[80:81] op_sel_hi:[1,0,1]
	v_mov_b32_e32 v16, v79
	v_pk_fma_f32 v[66:67], v[8:9], v[16:17], v[88:89] op_sel_hi:[1,0,1]
	v_pk_fma_f32 v[68:69], v[6:7], v[16:17], v[90:91] op_sel_hi:[1,0,1]
	v_mov_b32_e32 v16, v93
	v_pk_fma_f32 v[48:49], v[8:9], v[16:17], v[48:49] op_sel_hi:[1,0,1]
	v_pk_fma_f32 v[54:55], v[6:7], v[16:17], v[54:55] op_sel_hi:[1,0,1]
	v_mov_b32_e32 v16, v101
	v_pk_fma_f32 v[4:5], v[8:9], v[16:17], v[4:5] op_sel_hi:[1,0,1]
	v_pk_fma_f32 v[2:3], v[6:7], v[16:17], v[2:3] op_sel_hi:[1,0,1]
	v_mov_b32_e32 v16, v59
	s_waitcnt vmcnt(5)
	v_pk_fma_f32 v[6:7], v[42:43], v[58:59], v[50:51] op_sel_hi:[1,0,1]
	v_pk_fma_f32 v[8:9], v[40:41], v[58:59], v[52:53] op_sel_hi:[1,0,1]
	v_pk_fma_f32 v[50:51], v[42:43], v[70:71], v[56:57] op_sel_hi:[1,0,1]
	v_pk_fma_f32 v[52:53], v[40:41], v[70:71], v[60:61] op_sel_hi:[1,0,1]
	v_pk_fma_f32 v[56:57], v[42:43], v[82:83], v[66:67] op_sel_hi:[1,0,1]
	v_pk_fma_f32 v[60:61], v[40:41], v[82:83], v[68:69] op_sel_hi:[1,0,1]
	v_pk_fma_f32 v[48:49], v[42:43], v[94:95], v[48:49] op_sel_hi:[1,0,1]
	s_waitcnt vmcnt(4)
	v_pk_fma_f32 v[6:7], v[30:31], v[16:17], v[6:7] op_sel_hi:[1,0,1]
	v_pk_fma_f32 v[8:9], v[28:29], v[16:17], v[8:9] op_sel_hi:[1,0,1]
	v_mov_b32_e32 v16, v71
	v_pk_fma_f32 v[54:55], v[40:41], v[94:95], v[54:55] op_sel_hi:[1,0,1]
	s_waitcnt lgkmcnt(2)
	v_pk_fma_f32 v[4:5], v[42:43], v[26:27], v[4:5] op_sel_hi:[1,0,1]
	v_pk_fma_f32 v[2:3], v[40:41], v[26:27], v[2:3] op_sel_hi:[1,0,1]
	v_pk_fma_f32 v[40:41], v[30:31], v[16:17], v[50:51] op_sel_hi:[1,0,1]
	v_pk_fma_f32 v[42:43], v[28:29], v[16:17], v[52:53] op_sel_hi:[1,0,1]
	v_mov_b32_e32 v16, v83
	v_pk_fma_f32 v[50:51], v[30:31], v[16:17], v[56:57] op_sel_hi:[1,0,1]
	v_pk_fma_f32 v[52:53], v[28:29], v[16:17], v[60:61] op_sel_hi:[1,0,1]
	v_mov_b32_e32 v16, v95
	v_pk_fma_f32 v[48:49], v[30:31], v[16:17], v[48:49] op_sel_hi:[1,0,1]
	v_pk_fma_f32 v[54:55], v[28:29], v[16:17], v[54:55] op_sel_hi:[1,0,1]
	v_mov_b32_e32 v16, v27
	v_pk_fma_f32 v[2:3], v[28:29], v[16:17], v[2:3] op_sel_hi:[1,0,1]
	s_waitcnt vmcnt(3)
	v_pk_fma_f32 v[6:7], v[12:13], v[62:63], v[6:7] op_sel_hi:[1,0,1]
	v_pk_fma_f32 v[8:9], v[10:11], v[62:63], v[8:9] op_sel_hi:[1,0,1]
	v_pk_fma_f32 v[26:27], v[12:13], v[72:73], v[40:41] op_sel_hi:[1,0,1]
	v_pk_fma_f32 v[28:29], v[10:11], v[72:73], v[42:43] op_sel_hi:[1,0,1]
	v_pk_fma_f32 v[40:41], v[10:11], v[84:85], v[52:53] op_sel_hi:[1,0,1]
	v_pk_fma_f32 v[42:43], v[12:13], v[96:97], v[48:49] op_sel_hi:[1,0,1]
	v_pk_fma_f32 v[48:49], v[10:11], v[96:97], v[54:55] op_sel_hi:[1,0,1]
	s_waitcnt lgkmcnt(1)
	v_pk_fma_f32 v[2:3], v[10:11], v[102:103], v[2:3] op_sel_hi:[1,0,1]
	v_mov_b32_e32 v10, v63
	v_pk_fma_f32 v[4:5], v[30:31], v[16:17], v[4:5] op_sel_hi:[1,0,1]
	v_pk_fma_f32 v[30:31], v[12:13], v[84:85], v[50:51] op_sel_hi:[1,0,1]
	s_waitcnt vmcnt(2)
	v_pk_fma_f32 v[6:7], v[38:39], v[10:11], v[6:7] op_sel_hi:[1,0,1]
	v_pk_fma_f32 v[8:9], v[36:37], v[10:11], v[8:9] op_sel_hi:[1,0,1]
	v_mov_b32_e32 v10, v73
	v_mov_b32_e32 v16, v85
	v_pk_fma_f32 v[4:5], v[12:13], v[102:103], v[4:5] op_sel_hi:[1,0,1]
	v_pk_fma_f32 v[12:13], v[38:39], v[10:11], v[26:27] op_sel_hi:[1,0,1]
	v_pk_fma_f32 v[10:11], v[36:37], v[10:11], v[28:29] op_sel_hi:[1,0,1]
	v_pk_fma_f32 v[26:27], v[38:39], v[16:17], v[30:31] op_sel_hi:[1,0,1]
	v_pk_fma_f32 v[28:29], v[36:37], v[16:17], v[40:41] op_sel_hi:[1,0,1]
	v_mov_b32_e32 v16, v97
	v_pk_fma_f32 v[30:31], v[38:39], v[16:17], v[42:43] op_sel_hi:[1,0,1]
	v_pk_fma_f32 v[40:41], v[36:37], v[16:17], v[48:49] op_sel_hi:[1,0,1]
	v_mov_b32_e32 v16, v103
	v_pk_fma_f32 v[2:3], v[36:37], v[16:17], v[2:3] op_sel_hi:[1,0,1]
	v_pk_fma_f32 v[4:5], v[38:39], v[16:17], v[4:5] op_sel_hi:[1,0,1]
	s_waitcnt vmcnt(1)
	v_pk_fma_f32 v[6:7], v[34:35], v[64:65], v[6:7] op_sel_hi:[1,0,1]
	s_waitcnt lgkmcnt(0)
	v_pk_fma_f32 v[38:39], v[32:33], v[104:105], v[2:3] op_sel_hi:[1,0,1]
	v_mov_b32_e32 v2, v65
	v_pk_fma_f32 v[8:9], v[32:33], v[64:65], v[8:9] op_sel_hi:[1,0,1]
	v_pk_fma_f32 v[12:13], v[34:35], v[74:75], v[12:13] op_sel_hi:[1,0,1]
	v_pk_fma_f32 v[10:11], v[32:33], v[74:75], v[10:11] op_sel_hi:[1,0,1]
	v_pk_fma_f32 v[26:27], v[34:35], v[86:87], v[26:27] op_sel_hi:[1,0,1]
	v_pk_fma_f32 v[30:31], v[34:35], v[98:99], v[30:31] op_sel_hi:[1,0,1]
	v_pk_fma_f32 v[34:35], v[34:35], v[104:105], v[4:5] op_sel_hi:[1,0,1]
	s_waitcnt vmcnt(0)
	v_pk_fma_f32 v[4:5], v[46:47], v[2:3], v[6:7] op_sel_hi:[1,0,1]
	v_mov_b32_e32 v6, v75
	v_pk_fma_f32 v[28:29], v[32:33], v[86:87], v[28:29] op_sel_hi:[1,0,1]
	v_pk_fma_f32 v[36:37], v[32:33], v[98:99], v[40:41] op_sel_hi:[1,0,1]
	v_pk_fma_f32 v[2:3], v[44:45], v[2:3], v[8:9] op_sel_hi:[1,0,1]
	v_pk_fma_f32 v[8:9], v[46:47], v[6:7], v[12:13] op_sel_hi:[1,0,1]
	v_pk_fma_f32 v[6:7], v[44:45], v[6:7], v[10:11] op_sel_hi:[1,0,1]
	v_mov_b32_e32 v10, v87
	v_mov_b32_e32 v16, v99
	v_pk_fma_f32 v[12:13], v[46:47], v[10:11], v[26:27] op_sel_hi:[1,0,1]
	v_pk_fma_f32 v[10:11], v[44:45], v[10:11], v[28:29] op_sel_hi:[1,0,1]
	v_pk_fma_f32 v[28:29], v[46:47], v[16:17], v[30:31] op_sel_hi:[1,0,1]
	v_pk_fma_f32 v[26:27], v[44:45], v[16:17], v[36:37] op_sel_hi:[1,0,1]
	v_mov_b32_e32 v16, v105
	v_pk_fma_f32 v[32:33], v[46:47], v[16:17], v[34:35] op_sel_hi:[1,0,1]
	v_pk_fma_f32 v[30:31], v[44:45], v[16:17], v[38:39] op_sel_hi:[1,0,1]
	ds_write_b128 v21, v[2:5] offset:20480
	ds_write_b128 v21, v[6:9] offset:20608
	ds_write_b128 v21, v[10:13] offset:20736
	ds_write_b128 v21, v[26:29] offset:20864
	ds_write_b128 v21, v[30:33] offset:20992
	s_waitcnt lgkmcnt(0)
	s_barrier
	s_and_saveexec_b64 s[20:21], s[2:3]
	s_cbranch_execz .LBB0_23
	v_mov_b32_e32 v2, 0
	s_movk_i32 s13, 0x5000

.LBB0_410:
	s_mul_hi_i32 s6, s26, 0x2aaaaaab
	s_lshr_b32 s7, s6, 31
	s_ashr_i32 s6, s6, 5
	s_add_i32 s6, s6, s7
	s_mul_i32 s7, s6, 0xc0
	s_sub_i32 s24, s26, s7
	s_ashr_i32 s7, s6, 31
	s_lshl_b64 s[16:17], s[6:7], 10
	v_lshl_add_u64 v[0:1], s[16:17], 0, v[56:57]
	v_mov_b64_e32 v[2:3], s[18:19]
	s_lshl_b32 s14, s24, 5
	v_mad_u64_u32 v[2:3], s[16:17], v0, s39, v[2:3]
	v_mad_i32_i24 v3, v1, s39, v3
	s_ashr_i32 s15, s14, 31
	v_lshl_add_u64 v[0:1], s[14:15], 2, v[2:3]
	v_lshl_add_u64 v[0:1], v[0:1], 0, v[96:97]
	s_mov_b32 s7, 0x180000
	v_add_co_u32_e32 v2, vcc, s7, v0
	global_load_dwordx4 v[62:65], v[0:1], off nt
	s_nop 0
	v_addc_co_u32_e32 v3, vcc, 0, v1, vcc
	global_load_dwordx4 v[66:69], v[2:3], off nt
	s_mov_b32 s7, 0x300000
	v_add_co_u32_e32 v2, vcc, s7, v0
	s_mov_b32 s7, 0x480000
	s_nop 0
	v_addc_co_u32_e32 v3, vcc, 0, v1, vcc
	global_load_dwordx4 v[52:55], v[2:3], off nt
	v_add_co_u32_e32 v2, vcc, s7, v0
	s_mov_b32 s7, 0x600000
	s_nop 0
	v_addc_co_u32_e32 v3, vcc, 0, v1, vcc
	global_load_dwordx4 v[48:51], v[2:3], off nt
	v_add_co_u32_e32 v2, vcc, s7, v0
	s_mov_b32 s7, 0x780000
	s_nop 0
	v_addc_co_u32_e32 v3, vcc, 0, v1, vcc
	global_load_dwordx4 v[44:47], v[2:3], off nt
	v_add_co_u32_e32 v2, vcc, s7, v0
	s_mov_b32 s7, 0x900000
	s_nop 0
	v_addc_co_u32_e32 v3, vcc, 0, v1, vcc
	global_load_dwordx4 v[40:43], v[2:3], off nt
	v_add_co_u32_e32 v2, vcc, s7, v0
	s_mov_b32 s7, 0xa80000
	s_nop 0
	v_addc_co_u32_e32 v3, vcc, 0, v1, vcc
	global_load_dwordx4 v[36:39], v[2:3], off nt
	v_add_co_u32_e32 v2, vcc, s7, v0
	s_mov_b32 s7, 0xc00000
	s_nop 0
	v_addc_co_u32_e32 v3, vcc, 0, v1, vcc
	global_load_dwordx4 v[32:35], v[2:3], off nt
	v_add_co_u32_e32 v2, vcc, s7, v0
	s_mov_b32 s7, 0xd80000
	s_nop 0
	v_addc_co_u32_e32 v3, vcc, 0, v1, vcc
	global_load_dwordx4 v[28:31], v[2:3], off nt
	v_add_co_u32_e32 v2, vcc, s7, v0
	s_mov_b32 s7, 0xf00000
	s_nop 0
	v_addc_co_u32_e32 v3, vcc, 0, v1, vcc
	global_load_dwordx4 v[24:27], v[2:3], off nt
	v_add_co_u32_e32 v2, vcc, s7, v0
	s_mov_b32 s7, 0x1080000
	s_nop 0
	v_addc_co_u32_e32 v3, vcc, 0, v1, vcc
	global_load_dwordx4 v[20:23], v[2:3], off nt
	v_add_co_u32_e32 v2, vcc, s7, v0
	ds_read2st64_b32 v[70:71], v59 offset1:1
	ds_read2st64_b32 v[78:79], v59 offset0:16 offset1:17
	ds_read2st64_b32 v[84:85], v59 offset0:32 offset1:33
	ds_read2st64_b32 v[90:91], v59 offset0:48 offset1:49
	v_addc_co_u32_e32 v3, vcc, 0, v1, vcc
	global_load_dwordx4 v[16:19], v[2:3], off nt
	s_mov_b32 s7, 0x1200000
	v_add_co_u32_e32 v2, vcc, s7, v0
	ds_read2st64_b32 v[98:99], v59 offset0:64 offset1:65
	s_nop 0
	v_addc_co_u32_e32 v3, vcc, 0, v1, vcc
	global_load_dwordx4 v[12:15], v[2:3], off nt
	s_mov_b32 s7, 0x1380000
	v_add_co_u32_e32 v2, vcc, s7, v0
	s_mov_b32 s7, 0x1500000
	s_nop 0
	v_addc_co_u32_e32 v3, vcc, 0, v1, vcc
	s_waitcnt vmcnt(12) lgkmcnt(4)
	v_pk_fma_f32 v[72:73], v[64:65], v[70:71], 0 op_sel_hi:[1,0,0]
	v_pk_fma_f32 v[76:77], v[62:63], v[70:71], 0 op_sel_hi:[1,0,0]
	v_mov_b32_e32 v70, v71
	s_waitcnt lgkmcnt(3)
	v_pk_fma_f32 v[80:81], v[64:65], v[78:79], 0 op_sel_hi:[1,0,0]
	s_waitcnt vmcnt(11)
	v_pk_fma_f32 v[72:73], v[68:69], v[70:71], v[72:73] op_sel_hi:[1,0,1]
	v_pk_fma_f32 v[70:71], v[66:67], v[70:71], v[76:77] op_sel_hi:[1,0,1]
	v_mov_b32_e32 v76, v79
	v_pk_fma_f32 v[82:83], v[62:63], v[78:79], 0 op_sel_hi:[1,0,0]
	s_waitcnt lgkmcnt(2)
	v_pk_fma_f32 v[86:87], v[64:65], v[84:85], 0 op_sel_hi:[1,0,0]
	v_pk_fma_f32 v[88:89], v[62:63], v[84:85], 0 op_sel_hi:[1,0,0]
	v_pk_fma_f32 v[78:79], v[68:69], v[76:77], v[80:81] op_sel_hi:[1,0,1]
	v_mov_b32_e32 v80, v85
	s_waitcnt lgkmcnt(1)
	v_pk_fma_f32 v[92:93], v[64:65], v[90:91], 0 op_sel_hi:[1,0,0]
	v_pk_fma_f32 v[94:95], v[62:63], v[90:91], 0 op_sel_hi:[1,0,0]
	s_waitcnt lgkmcnt(0)
	v_pk_fma_f32 v[62:63], v[62:63], v[98:99], 0 op_sel_hi:[1,0,0]
	v_pk_fma_f32 v[76:77], v[66:67], v[76:77], v[82:83] op_sel_hi:[1,0,1]
	v_pk_fma_f32 v[82:83], v[68:69], v[80:81], v[86:87] op_sel_hi:[1,0,1]
	v_pk_fma_f32 v[80:81], v[66:67], v[80:81], v[88:89] op_sel_hi:[1,0,1]
	v_mov_b32_e32 v84, v91
	v_mov_b32_e32 v88, v99
	v_pk_fma_f32 v[86:87], v[68:69], v[84:85], v[92:93] op_sel_hi:[1,0,1]
	v_pk_fma_f32 v[84:85], v[66:67], v[84:85], v[94:95] op_sel_hi:[1,0,1]
	v_pk_fma_f32 v[62:63], v[66:67], v[88:89], v[62:63] op_sel_hi:[1,0,1]
	ds_read2st64_b32 v[66:67], v59 offset0:2 offset1:3
	ds_read2st64_b32 v[92:93], v59 offset0:66 offset1:67
	global_load_dwordx4 v[8:11], v[2:3], off nt
	v_pk_fma_f32 v[64:65], v[64:65], v[98:99], 0 op_sel_hi:[1,0,0]
	ds_read2st64_b32 v[90:91], v59 offset0:50 offset1:51
	v_pk_fma_f32 v[64:65], v[68:69], v[88:89], v[64:65] op_sel_hi:[1,0,1]
	ds_read2st64_b32 v[88:89], v59 offset0:34 offset1:35
	s_waitcnt vmcnt(11) lgkmcnt(3)
	v_pk_fma_f32 v[68:69], v[54:55], v[66:67], v[72:73] op_sel_hi:[1,0,1]
	ds_read2st64_b32 v[72:73], v59 offset0:18 offset1:19
	v_add_co_u32_e32 v2, vcc, s7, v0
	v_pk_fma_f32 v[70:71], v[52:53], v[66:67], v[70:71] op_sel_hi:[1,0,1]
	s_nop 0
	v_addc_co_u32_e32 v3, vcc, 0, v1, vcc
	global_load_dwordx4 v[4:7], v[2:3], off nt
	s_waitcnt lgkmcnt(0)
	v_pk_fma_f32 v[76:77], v[52:53], v[72:73], v[76:77] op_sel_hi:[1,0,1]
	v_pk_fma_f32 v[80:81], v[52:53], v[88:89], v[80:81] op_sel_hi:[1,0,1]
	v_pk_fma_f32 v[84:85], v[52:53], v[90:91], v[84:85] op_sel_hi:[1,0,1]
	v_pk_fma_f32 v[52:53], v[52:53], v[92:93], v[62:63] op_sel_hi:[1,0,1]
	v_mov_b32_e32 v62, v67
	v_pk_fma_f32 v[78:79], v[54:55], v[72:73], v[78:79] op_sel_hi:[1,0,1]
	v_pk_fma_f32 v[82:83], v[54:55], v[88:89], v[82:83] op_sel_hi:[1,0,1]
	v_pk_fma_f32 v[86:87], v[54:55], v[90:91], v[86:87] op_sel_hi:[1,0,1]
	v_pk_fma_f32 v[54:55], v[54:55], v[92:93], v[64:65] op_sel_hi:[1,0,1]
	s_waitcnt vmcnt(11)
	v_pk_fma_f32 v[64:65], v[50:51], v[62:63], v[68:69] op_sel_hi:[1,0,1]
	v_pk_fma_f32 v[62:63], v[48:49], v[62:63], v[70:71] op_sel_hi:[1,0,1]
	v_mov_b32_e32 v66, v73
	v_mov_b32_e32 v70, v89
	v_pk_fma_f32 v[68:69], v[50:51], v[66:67], v[78:79] op_sel_hi:[1,0,1]
	v_pk_fma_f32 v[66:67], v[48:49], v[66:67], v[76:77] op_sel_hi:[1,0,1]
	v_pk_fma_f32 v[72:73], v[50:51], v[70:71], v[82:83] op_sel_hi:[1,0,1]
	v_pk_fma_f32 v[70:71], v[48:49], v[70:71], v[80:81] op_sel_hi:[1,0,1]
	v_mov_b32_e32 v76, v91
	v_mov_b32_e32 v80, v93
	v_pk_fma_f32 v[78:79], v[50:51], v[76:77], v[86:87] op_sel_hi:[1,0,1]
	v_pk_fma_f32 v[76:77], v[48:49], v[76:77], v[84:85] op_sel_hi:[1,0,1]
	v_pk_fma_f32 v[48:49], v[48:49], v[80:81], v[52:53] op_sel_hi:[1,0,1]
	ds_read2st64_b32 v[52:53], v59 offset0:4 offset1:5
	ds_read2st64_b32 v[84:85], v59 offset0:68 offset1:69
	s_mov_b32 s7, 0x1680000
	v_add_co_u32_e32 v0, vcc, s7, v0
	v_pk_fma_f32 v[50:51], v[50:51], v[80:81], v[54:55] op_sel_hi:[1,0,1]
	ds_read2st64_b32 v[80:81], v59 offset0:36 offset1:37
	s_waitcnt vmcnt(10) lgkmcnt(2)
	v_pk_fma_f32 v[54:55], v[46:47], v[52:53], v[64:65] op_sel_hi:[1,0,1]
	ds_read2st64_b32 v[64:65], v59 offset0:20 offset1:21
	ds_read2st64_b32 v[82:83], v59 offset0:52 offset1:53
	v_addc_co_u32_e32 v1, vcc, 0, v1, vcc
	global_load_dwordx4 v[0:3], v[0:1], off nt
	v_pk_fma_f32 v[62:63], v[44:45], v[52:53], v[62:63] op_sel_hi:[1,0,1]
	s_waitcnt lgkmcnt(1)
	v_pk_fma_f32 v[68:69], v[46:47], v[64:65], v[68:69] op_sel_hi:[1,0,1]
	v_pk_fma_f32 v[66:67], v[44:45], v[64:65], v[66:67] op_sel_hi:[1,0,1]
	v_pk_fma_f32 v[70:71], v[44:45], v[80:81], v[70:71] op_sel_hi:[1,0,1]
	s_waitcnt lgkmcnt(0)
	v_pk_fma_f32 v[76:77], v[44:45], v[82:83], v[76:77] op_sel_hi:[1,0,1]
	v_pk_fma_f32 v[44:45], v[44:45], v[84:85], v[48:49] op_sel_hi:[1,0,1]
	v_mov_b32_e32 v48, v53
	v_mov_b32_e32 v52, v65
	v_pk_fma_f32 v[72:73], v[46:47], v[80:81], v[72:73] op_sel_hi:[1,0,1]
	v_pk_fma_f32 v[78:79], v[46:47], v[82:83], v[78:79] op_sel_hi:[1,0,1]
	v_pk_fma_f32 v[46:47], v[46:47], v[84:85], v[50:51] op_sel_hi:[1,0,1]
	s_waitcnt vmcnt(10)
	v_pk_fma_f32 v[50:51], v[42:43], v[48:49], v[54:55] op_sel_hi:[1,0,1]
	v_pk_fma_f32 v[48:49], v[40:41], v[48:49], v[62:63] op_sel_hi:[1,0,1]
	v_pk_fma_f32 v[54:55], v[42:43], v[52:53], v[68:69] op_sel_hi:[1,0,1]
	v_pk_fma_f32 v[62:63], v[40:41], v[52:53], v[66:67] op_sel_hi:[1,0,1]
	v_mov_b32_e32 v52, v81
	v_pk_fma_f32 v[64:65], v[42:43], v[52:53], v[72:73] op_sel_hi:[1,0,1]
	v_pk_fma_f32 v[66:67], v[40:41], v[52:53], v[70:71] op_sel_hi:[1,0,1]
	v_mov_b32_e32 v52, v83
	v_pk_fma_f32 v[70:71], v[42:43], v[52:53], v[78:79] op_sel_hi:[1,0,1]
	v_pk_fma_f32 v[72:73], v[40:41], v[52:53], v[76:77] op_sel_hi:[1,0,1]
	v_mov_b32_e32 v52, v85
	v_pk_fma_f32 v[40:41], v[40:41], v[52:53], v[44:45] op_sel_hi:[1,0,1]
	ds_read2st64_b32 v[44:45], v59 offset0:6 offset1:7
	ds_read2st64_b32 v[68:69], v59 offset0:54 offset1:55
	v_pk_fma_f32 v[42:43], v[42:43], v[52:53], v[46:47] op_sel_hi:[1,0,1]
	ds_read2st64_b32 v[76:77], v59 offset0:70 offset1:71
	s_waitcnt vmcnt(9) lgkmcnt(2)
	v_pk_fma_f32 v[46:47], v[38:39], v[44:45], v[50:51] op_sel_hi:[1,0,1]
	ds_read2st64_b32 v[50:51], v59 offset0:22 offset1:23
	v_pk_fma_f32 v[48:49], v[36:37], v[44:45], v[48:49] op_sel_hi:[1,0,1]
	s_waitcnt lgkmcnt(2)
	v_pk_fma_f32 v[72:73], v[36:37], v[68:69], v[72:73] op_sel_hi:[1,0,1]
	v_pk_fma_f32 v[70:71], v[38:39], v[68:69], v[70:71] op_sel_hi:[1,0,1]
	s_waitcnt lgkmcnt(0)
	v_pk_fma_f32 v[52:53], v[38:39], v[50:51], v[54:55] op_sel_hi:[1,0,1]
	v_pk_fma_f32 v[54:55], v[36:37], v[50:51], v[62:63] op_sel_hi:[1,0,1]
	ds_read2st64_b32 v[62:63], v59 offset0:38 offset1:39
	v_mov_b32_e32 v44, v51
	s_waitcnt lgkmcnt(0)
	v_pk_fma_f32 v[66:67], v[36:37], v[62:63], v[66:67] op_sel_hi:[1,0,1]
	v_pk_fma_f32 v[36:37], v[36:37], v[76:77], v[40:41] op_sel_hi:[1,0,1]
	v_mov_b32_e32 v40, v45
	v_pk_fma_f32 v[64:65], v[38:39], v[62:63], v[64:65] op_sel_hi:[1,0,1]
	v_pk_fma_f32 v[38:39], v[38:39], v[76:77], v[42:43] op_sel_hi:[1,0,1]
	s_waitcnt vmcnt(8)
	v_pk_fma_f32 v[42:43], v[34:35], v[40:41], v[46:47] op_sel_hi:[1,0,1]
	v_pk_fma_f32 v[40:41], v[32:33], v[40:41], v[48:49] op_sel_hi:[1,0,1]
	v_pk_fma_f32 v[46:47], v[34:35], v[44:45], v[52:53] op_sel_hi:[1,0,1]
	v_mov_b32_e32 v48, v63
	v_mov_b32_e32 v52, v69
	v_mov_b32_e32 v62, v77
	v_pk_fma_f32 v[44:45], v[32:33], v[44:45], v[54:55] op_sel_hi:[1,0,1]
	v_pk_fma_f32 v[50:51], v[34:35], v[48:49], v[64:65] op_sel_hi:[1,0,1]
	v_pk_fma_f32 v[48:49], v[32:33], v[48:49], v[66:67] op_sel_hi:[1,0,1]
	v_pk_fma_f32 v[54:55], v[34:35], v[52:53], v[70:71] op_sel_hi:[1,0,1]
	v_pk_fma_f32 v[52:53], v[32:33], v[52:53], v[72:73] op_sel_hi:[1,0,1]
	v_pk_fma_f32 v[32:33], v[32:33], v[62:63], v[36:37] op_sel_hi:[1,0,1]
	ds_read2st64_b32 v[36:37], v59 offset0:8 offset1:9
	ds_read2st64_b32 v[66:67], v59 offset0:72 offset1:73
	v_pk_fma_f32 v[34:35], v[34:35], v[62:63], v[38:39] op_sel_hi:[1,0,1]
	ds_read2st64_b32 v[62:63], v59 offset0:40 offset1:41
	ds_read2st64_b32 v[64:65], v59 offset0:56 offset1:57
	s_waitcnt vmcnt(7) lgkmcnt(3)
	v_pk_fma_f32 v[38:39], v[30:31], v[36:37], v[42:43] op_sel_hi:[1,0,1]
	ds_read2st64_b32 v[42:43], v59 offset0:24 offset1:25
	v_pk_fma_f32 v[40:41], v[28:29], v[36:37], v[40:41] op_sel_hi:[1,0,1]
	s_waitcnt lgkmcnt(2)
	v_pk_fma_f32 v[48:49], v[28:29], v[62:63], v[48:49] op_sel_hi:[1,0,1]
	s_waitcnt lgkmcnt(1)
	v_pk_fma_f32 v[52:53], v[28:29], v[64:65], v[52:53] op_sel_hi:[1,0,1]
	v_pk_fma_f32 v[50:51], v[30:31], v[62:63], v[50:51] op_sel_hi:[1,0,1]
	s_waitcnt lgkmcnt(0)
	v_pk_fma_f32 v[44:45], v[28:29], v[42:43], v[44:45] op_sel_hi:[1,0,1]
	v_pk_fma_f32 v[28:29], v[28:29], v[66:67], v[32:33] op_sel_hi:[1,0,1]
	v_mov_b32_e32 v32, v37
	v_pk_fma_f32 v[46:47], v[30:31], v[42:43], v[46:47] op_sel_hi:[1,0,1]
	v_pk_fma_f32 v[54:55], v[30:31], v[64:65], v[54:55] op_sel_hi:[1,0,1]
	v_pk_fma_f32 v[30:31], v[30:31], v[66:67], v[34:35] op_sel_hi:[1,0,1]
	s_waitcnt vmcnt(6)
	v_pk_fma_f32 v[34:35], v[26:27], v[32:33], v[38:39] op_sel_hi:[1,0,1]
	v_pk_fma_f32 v[32:33], v[24:25], v[32:33], v[40:41] op_sel_hi:[1,0,1]
	v_mov_b32_e32 v36, v43
	v_mov_b32_e32 v40, v63
	v_pk_fma_f32 v[38:39], v[26:27], v[36:37], v[46:47] op_sel_hi:[1,0,1]
	v_pk_fma_f32 v[36:37], v[24:25], v[36:37], v[44:45] op_sel_hi:[1,0,1]
	v_pk_fma_f32 v[42:43], v[26:27], v[40:41], v[50:51] op_sel_hi:[1,0,1]
	v_pk_fma_f32 v[40:41], v[24:25], v[40:41], v[48:49] op_sel_hi:[1,0,1]
	v_mov_b32_e32 v44, v65
	v_mov_b32_e32 v48, v67
	v_pk_fma_f32 v[46:47], v[26:27], v[44:45], v[54:55] op_sel_hi:[1,0,1]
	v_pk_fma_f32 v[44:45], v[24:25], v[44:45], v[52:53] op_sel_hi:[1,0,1]
	v_pk_fma_f32 v[24:25], v[24:25], v[48:49], v[28:29] op_sel_hi:[1,0,1]
	ds_read2st64_b32 v[28:29], v59 offset0:10 offset1:11
	ds_read2st64_b32 v[52:53], v59 offset0:74 offset1:75
	v_pk_fma_f32 v[26:27], v[26:27], v[48:49], v[30:31] op_sel_hi:[1,0,1]
	ds_read2st64_b32 v[48:49], v59 offset0:42 offset1:43
	ds_read2st64_b32 v[50:51], v59 offset0:58 offset1:59
	s_waitcnt vmcnt(5) lgkmcnt(3)
	v_pk_fma_f32 v[30:31], v[22:23], v[28:29], v[34:35] op_sel_hi:[1,0,1]
	ds_read2st64_b32 v[34:35], v59 offset0:26 offset1:27
	v_pk_fma_f32 v[32:33], v[20:21], v[28:29], v[32:33] op_sel_hi:[1,0,1]
	s_waitcnt lgkmcnt(2)
	v_pk_fma_f32 v[40:41], v[20:21], v[48:49], v[40:41] op_sel_hi:[1,0,1]
	s_waitcnt lgkmcnt(1)
	v_pk_fma_f32 v[44:45], v[20:21], v[50:51], v[44:45] op_sel_hi:[1,0,1]
	v_pk_fma_f32 v[42:43], v[22:23], v[48:49], v[42:43] op_sel_hi:[1,0,1]
	s_waitcnt lgkmcnt(0)
	v_pk_fma_f32 v[36:37], v[20:21], v[34:35], v[36:37] op_sel_hi:[1,0,1]
	v_pk_fma_f32 v[20:21], v[20:21], v[52:53], v[24:25] op_sel_hi:[1,0,1]
	v_mov_b32_e32 v24, v29
	v_pk_fma_f32 v[38:39], v[22:23], v[34:35], v[38:39] op_sel_hi:[1,0,1]
	v_pk_fma_f32 v[46:47], v[22:23], v[50:51], v[46:47] op_sel_hi:[1,0,1]
	v_pk_fma_f32 v[22:23], v[22:23], v[52:53], v[26:27] op_sel_hi:[1,0,1]
	s_waitcnt vmcnt(4)
	v_pk_fma_f32 v[26:27], v[18:19], v[24:25], v[30:31] op_sel_hi:[1,0,1]
	v_pk_fma_f32 v[24:25], v[16:17], v[24:25], v[32:33] op_sel_hi:[1,0,1]
	v_mov_b32_e32 v28, v35
	v_mov_b32_e32 v32, v49
	v_pk_fma_f32 v[30:31], v[18:19], v[28:29], v[38:39] op_sel_hi:[1,0,1]
	v_pk_fma_f32 v[28:29], v[16:17], v[28:29], v[36:37] op_sel_hi:[1,0,1]
	v_pk_fma_f32 v[34:35], v[18:19], v[32:33], v[42:43] op_sel_hi:[1,0,1]
	v_pk_fma_f32 v[32:33], v[16:17], v[32:33], v[40:41] op_sel_hi:[1,0,1]
	v_mov_b32_e32 v36, v51
	v_mov_b32_e32 v40, v53
	v_pk_fma_f32 v[38:39], v[18:19], v[36:37], v[46:47] op_sel_hi:[1,0,1]
	v_pk_fma_f32 v[36:37], v[16:17], v[36:37], v[44:45] op_sel_hi:[1,0,1]
	v_pk_fma_f32 v[16:17], v[16:17], v[40:41], v[20:21] op_sel_hi:[1,0,1]
	ds_read2st64_b32 v[20:21], v59 offset0:12 offset1:13
	ds_read2st64_b32 v[44:45], v59 offset0:76 offset1:77
	v_pk_fma_f32 v[18:19], v[18:19], v[40:41], v[22:23] op_sel_hi:[1,0,1]
	ds_read2st64_b32 v[40:41], v59 offset0:44 offset1:45
	ds_read2st64_b32 v[42:43], v59 offset0:60 offset1:61
	s_waitcnt vmcnt(3) lgkmcnt(3)
	v_pk_fma_f32 v[22:23], v[14:15], v[20:21], v[26:27] op_sel_hi:[1,0,1]
	ds_read2st64_b32 v[26:27], v59 offset0:28 offset1:29
	v_pk_fma_f32 v[24:25], v[12:13], v[20:21], v[24:25] op_sel_hi:[1,0,1]
	s_waitcnt lgkmcnt(2)
	v_pk_fma_f32 v[32:33], v[12:13], v[40:41], v[32:33] op_sel_hi:[1,0,1]
	s_waitcnt lgkmcnt(1)
	v_pk_fma_f32 v[36:37], v[12:13], v[42:43], v[36:37] op_sel_hi:[1,0,1]
	v_pk_fma_f32 v[34:35], v[14:15], v[40:41], v[34:35] op_sel_hi:[1,0,1]
	s_waitcnt lgkmcnt(0)
	v_pk_fma_f32 v[30:31], v[14:15], v[26:27], v[30:31] op_sel_hi:[1,0,1]
	v_pk_fma_f32 v[28:29], v[12:13], v[26:27], v[28:29] op_sel_hi:[1,0,1]
	v_pk_fma_f32 v[12:13], v[12:13], v[44:45], v[16:17] op_sel_hi:[1,0,1]
	v_mov_b32_e32 v16, v21
	v_mov_b32_e32 v20, v27
	v_pk_fma_f32 v[38:39], v[14:15], v[42:43], v[38:39] op_sel_hi:[1,0,1]
	v_pk_fma_f32 v[14:15], v[14:15], v[44:45], v[18:19] op_sel_hi:[1,0,1]
	s_waitcnt vmcnt(2)
	v_pk_fma_f32 v[18:19], v[10:11], v[16:17], v[22:23] op_sel_hi:[1,0,1]
	v_pk_fma_f32 v[16:17], v[8:9], v[16:17], v[24:25] op_sel_hi:[1,0,1]
	v_pk_fma_f32 v[22:23], v[10:11], v[20:21], v[30:31] op_sel_hi:[1,0,1]
	v_pk_fma_f32 v[24:25], v[8:9], v[20:21], v[28:29] op_sel_hi:[1,0,1]
	v_mov_b32_e32 v20, v41
	v_pk_fma_f32 v[26:27], v[10:11], v[20:21], v[34:35] op_sel_hi:[1,0,1]
	v_pk_fma_f32 v[28:29], v[8:9], v[20:21], v[32:33] op_sel_hi:[1,0,1]
	v_mov_b32_e32 v20, v43
	v_pk_fma_f32 v[32:33], v[10:11], v[20:21], v[38:39] op_sel_hi:[1,0,1]
	v_pk_fma_f32 v[34:35], v[8:9], v[20:21], v[36:37] op_sel_hi:[1,0,1]
	v_mov_b32_e32 v20, v45
	v_pk_fma_f32 v[8:9], v[8:9], v[20:21], v[12:13] op_sel_hi:[1,0,1]
	ds_read2st64_b32 v[12:13], v59 offset0:14 offset1:15
	ds_read2st64_b32 v[30:31], v59 offset0:62 offset1:63
	v_pk_fma_f32 v[10:11], v[10:11], v[20:21], v[14:15] op_sel_hi:[1,0,1]
	ds_read2st64_b32 v[36:37], v59 offset0:78 offset1:79
	s_waitcnt vmcnt(1) lgkmcnt(2)
	v_pk_fma_f32 v[14:15], v[6:7], v[12:13], v[18:19] op_sel_hi:[1,0,1]
	ds_read2st64_b32 v[18:19], v59 offset0:30 offset1:31
	v_pk_fma_f32 v[16:17], v[4:5], v[12:13], v[16:17] op_sel_hi:[1,0,1]
	s_waitcnt lgkmcnt(2)
	v_pk_fma_f32 v[34:35], v[4:5], v[30:31], v[34:35] op_sel_hi:[1,0,1]
	s_waitcnt lgkmcnt(1)
	v_pk_fma_f32 v[40:41], v[4:5], v[36:37], v[8:9] op_sel_hi:[1,0,1]
	v_pk_fma_f32 v[32:33], v[6:7], v[30:31], v[32:33] op_sel_hi:[1,0,1]
	s_waitcnt lgkmcnt(0)
	v_pk_fma_f32 v[20:21], v[6:7], v[18:19], v[22:23] op_sel_hi:[1,0,1]
	v_pk_fma_f32 v[22:23], v[4:5], v[18:19], v[24:25] op_sel_hi:[1,0,1]
	ds_read2st64_b32 v[24:25], v59 offset0:46 offset1:47
	v_mov_b32_e32 v8, v19
	v_pk_fma_f32 v[38:39], v[6:7], v[36:37], v[10:11] op_sel_hi:[1,0,1]
	s_waitcnt vmcnt(0)
	v_pk_fma_f32 v[10:11], v[2:3], v[8:9], v[20:21] op_sel_hi:[1,0,1]
	v_mov_b32_e32 v20, v37
	s_waitcnt lgkmcnt(0)
	v_pk_fma_f32 v[28:29], v[4:5], v[24:25], v[28:29] op_sel_hi:[1,0,1]
	v_mov_b32_e32 v4, v13
	v_pk_fma_f32 v[26:27], v[6:7], v[24:25], v[26:27] op_sel_hi:[1,0,1]
	v_pk_fma_f32 v[6:7], v[2:3], v[4:5], v[14:15] op_sel_hi:[1,0,1]
	v_pk_fma_f32 v[4:5], v[0:1], v[4:5], v[16:17] op_sel_hi:[1,0,1]
	v_mov_b32_e32 v12, v25
	v_mov_b32_e32 v16, v31
	v_pk_fma_f32 v[8:9], v[0:1], v[8:9], v[22:23] op_sel_hi:[1,0,1]
	v_pk_fma_f32 v[14:15], v[2:3], v[12:13], v[26:27] op_sel_hi:[1,0,1]
	v_pk_fma_f32 v[12:13], v[0:1], v[12:13], v[28:29] op_sel_hi:[1,0,1]
	v_pk_fma_f32 v[18:19], v[2:3], v[16:17], v[32:33] op_sel_hi:[1,0,1]
	v_pk_fma_f32 v[16:17], v[0:1], v[16:17], v[34:35] op_sel_hi:[1,0,1]
	v_pk_fma_f32 v[2:3], v[2:3], v[20:21], v[38:39] op_sel_hi:[1,0,1]
	v_pk_fma_f32 v[0:1], v[0:1], v[20:21], v[40:41] op_sel_hi:[1,0,1]
	ds_write_b128 v74, v[4:7] offset:20480
	ds_write_b128 v74, v[8:11] offset:20608
	ds_write_b128 v74, v[12:15] offset:20736
	ds_write_b128 v74, v[16:19] offset:20864
	ds_write_b128 v74, v[0:3] offset:20992
	s_waitcnt lgkmcnt(0)
	s_barrier
	s_and_saveexec_b64 s[16:17], s[2:3]
	s_cbranch_execz .LBB0_409
	v_mov_b32_e32 v0, 0
	s_movk_i32 s7, 0x5000
